# all 9 seams use lean barrier (L1 invalidate on wave 1 overlapped with sync); removed redundant fences in final-norm panel sync
# speedup vs baseline: 1.0086x; 1.0086x over previous
; DI unsigned xb_ld(unsigned* p)              { return __hip_atomic_load(p, __ATOMIC_RELAXED, __HIP_MEMORY_SCOPE_AGENT); }
; DI void xcd_barrier_complete(unsigned* bar, unsigned x, unsigned& nloc, unsigned& nx) {
;     const unsigned G = gridDim.x * gridDim.y * gridDim.z;
;     unsigned sum, cnt, mine, sp = 0u;
;     for (;;) {
;         sum = 0u; cnt = 0u; mine = 0u;
; #pragma unroll
;         for (unsigned j = 0; j < 16; ++j) { const unsigned c = xb_ld(&bar[XB_XCNT(j)]); sum += c; cnt += (c > 0u) ? 1u : 0u; mine = (j == x) ? c : mine; }
;         if (sum == G) break;
; DI void xcd_barrier(const XcdBarrier& b) {
;     asm volatile("s_waitcnt vmcnt(0)" ::: "memory");
;     __syncthreads();
;     if (threadIdx.x == 0) {
;         unsigned* bar = b.bar;
;         __builtin_amdgcn_s_waitcnt(0);
;         unsigned nloc = b.st[0], nx = b.st[1];
;         if (nloc == 0u) { xcd_barrier_complete(bar, b.x, nloc, nx); b.st[0] = nloc; b.st[1] = nx; }
.LBB0_154:
	s_cmp_gt_i32 s85, 1
	s_cselect_b64 s[0:1], -1, 0
	s_and_b64 s[4:5], s[26:27], s[0:1]
	s_andn2_b64 vcc, exec, s[4:5]
	s_cbranch_vccnz .LBB0_208
	s_waitcnt vmcnt(0)
	s_waitcnt lgkmcnt(0)
	s_barrier
	v_readlane_b32 s3, v254, 3
	s_nop 3
	s_cmp_lg_u32 s3, 1
	s_cbranch_scc1 .Lmb1_notw1
	buffer_inv sc1
	s_waitcnt vmcnt(0)
.Lmb1_notw1:
	s_mov_b64 s[4:5], exec
	v_readlane_b32 s6, v254, 1
	v_readlane_b32 s7, v254, 2
	s_and_b64 s[6:7], s[4:5], s[6:7]
	s_mov_b64 exec, s[6:7]
	s_cbranch_execz .LBB0_207
	s_add_i32 s3, 0, 0x20100
	v_mov_b32_e32 v0, s3
	s_waitcnt vmcnt(0) expcnt(0) lgkmcnt(0)
	ds_read_b32 v2, v0
	s_add_i32 s3, 0, 0x20104
	v_mov_b32_e32 v0, s3
	ds_read_b32 v0, v0
	s_waitcnt lgkmcnt(1)
	v_cmp_ne_u32_e32 vcc, 0, v2
	s_cbranch_vccnz .LBB0_171
	s_add_u32 s6, s88, 0x1000
	s_addc_u32 s7, s89, 0
	s_add_u32 s8, s88, 0x1100
	s_addc_u32 s9, s89, 0
	s_add_u32 s10, s88, 0x1200
	v_readlane_b32 s3, v254, 0
	s_addc_u32 s11, s89, 0
	s_mul_i32 s3, s59, s3
	s_add_u32 s12, s88, 0x1300
	s_mul_i32 s3, s3, s58
	s_addc_u32 s13, s89, 0
	s_mov_b32 s30, 1
	v_mov_b32_e32 v16, 0
	s_branch .LBB0_159

; DI unsigned xb_ld(unsigned* p)              { return __hip_atomic_load(p, __ATOMIC_RELAXED, __HIP_MEMORY_SCOPE_AGENT); }
; DI unsigned xb_add(unsigned* p, unsigned v) { return __hip_atomic_fetch_add(p, v, __ATOMIC_RELAXED, __HIP_MEMORY_SCOPE_AGENT); }
; #define XB_SPIN(cond, bar) do { unsigned _sp = 0; while (cond) { __builtin_amdgcn_s_sleep(1); \
;     if ((++_sp & 255u) == 0u) { if (xb_ld(&(bar)[XB_TMO])) break; if (_sp > XB_SPIN_CAP) { atomicAdd(&(bar)[XB_TMO], 1u); break; } } } } while (0)
; DI void xcd_barrier(const XcdBarrier& b) {
;     ...
;         unsigned nloc = b.st[0], nx = b.st[1];
;         if (nloc == 0u) { xcd_barrier_complete(bar, b.x, nloc, nx); b.st[0] = nloc; b.st[1] = nx; }
;         const unsigned old = xb_add(&bar[XB_XSUB(b.x)], 1u);
;         const unsigned gen = old / nloc;
;         if (old + 1u == (gen + 1u) * nloc) {
;             __builtin_amdgcn_fence(__ATOMIC_RELEASE, "agent");
;             asm volatile("s_waitcnt vmcnt(0)" ::: "memory");
;             const unsigned og = xb_add(&bar[XB_TOP], 1u);
;             const unsigned tg = og / nx;
;             if (og + 1u == (tg + 1u) * nx) xb_add(&bar[XB_TOPGEN], 1u);
;             else XB_SPIN(xb_ld(&bar[XB_TOPGEN]) == tg, bar);
;             __builtin_amdgcn_fence(__ATOMIC_ACQUIRE, "agent");
;             xb_add(&bar[XB_XGEN(b.x)], 1u);
;             asm volatile("s_waitcnt vmcnt(0)" ::: "memory");
.LBB0_171:
	v_mov_b32_e32 v0, 0x20100
	ds_read2_b32 v[2:3], v0 offset1:1
	s_add_u32 s10, s88, 0x3600
	s_addc_u32 s11, s89, 0
	s_lshl_b32 s22, s92, 8
	s_addk_i32 s22, 0x1400
	v_mov_b32_e32 v0, s22
	v_mov_b32_e32 v1, 1
	global_atomic_add v4, v0, v1, s[10:11] sc0
	s_waitcnt lgkmcnt(0)
	v_readfirstlane_b32 s12, v2
	v_readfirstlane_b32 s13, v3
	s_mul_i32 s12, s12, 1
	s_mul_i32 s13, s13, 1
	s_mov_b32 s23, 0
	s_waitcnt vmcnt(0)
	v_readfirstlane_b32 s3, v4
	s_add_i32 s3, s3, 1
	s_cmp_lg_u32 s3, s12
	s_cbranch_scc1 .Lmb1_wait
	buffer_wbl2 sc1
	s_waitcnt vmcnt(0)
	v_mov_b32_e32 v0, 0x3400
	global_atomic_add v4, v0, v1, s[10:11] sc0
	s_waitcnt vmcnt(0)
	v_readfirstlane_b32 s3, v4
	s_add_i32 s3, s3, 1
	s_cmp_lg_u32 s3, s13
	s_cbranch_scc1 .Lmb1_wait
	v_mov_b32_e32 v0, 0x2400
	global_atomic_add v0, v1, s[10:11]
	global_atomic_add v0, v1, s[10:11] offset:256
	global_atomic_add v0, v1, s[10:11] offset:512
	global_atomic_add v0, v1, s[10:11] offset:768
	global_atomic_add v0, v1, s[10:11] offset:1024
	global_atomic_add v0, v1, s[10:11] offset:1280
	global_atomic_add v0, v1, s[10:11] offset:1536
	global_atomic_add v0, v1, s[10:11] offset:1792
	global_atomic_add v0, v1, s[10:11] offset:2048
	global_atomic_add v0, v1, s[10:11] offset:2304
	global_atomic_add v0, v1, s[10:11] offset:2560
	global_atomic_add v0, v1, s[10:11] offset:2816
	global_atomic_add v0, v1, s[10:11] offset:3072
	global_atomic_add v0, v1, s[10:11] offset:3328
	global_atomic_add v0, v1, s[10:11] offset:3584
	global_atomic_add v0, v1, s[10:11] offset:3840
	s_branch .Lmb1_done

; DI unsigned xb_ld(unsigned* p)              { return __hip_atomic_load(p, __ATOMIC_RELAXED, __HIP_MEMORY_SCOPE_AGENT); }
; DI unsigned xb_add(unsigned* p, unsigned v) { return __hip_atomic_fetch_add(p, v, __ATOMIC_RELAXED, __HIP_MEMORY_SCOPE_AGENT); }
; #define XB_SPIN(cond, bar) do { unsigned _sp = 0; while (cond) { __builtin_amdgcn_s_sleep(1); \
;     if ((++_sp & 255u) == 0u) { if (xb_ld(&(bar)[XB_TMO])) break; if (_sp > XB_SPIN_CAP) { atomicAdd(&(bar)[XB_TMO], 1u); break; } } } } while (0)
; DI void xcd_barrier(const XcdBarrier& b) {
;     ...
;             __builtin_amdgcn_fence(__ATOMIC_ACQUIRE, "agent");
;             xb_add(&bar[XB_XGEN(b.x)], 1u);
;             asm volatile("s_waitcnt vmcnt(0)" ::: "memory");
;         } else {
;             XB_SPIN(xb_ld(&bar[XB_XGEN(b.x)]) == gen, bar);
;             __builtin_amdgcn_fence(__ATOMIC_ACQUIRE, "agent");
;             asm volatile("s_waitcnt vmcnt(0)" ::: "memory");
;         }
;     }
;     __syncthreads();
.Lmb1_got:
.Lmb1_done:
.LBB0_207:
	s_or_b64 exec, exec, s[4:5]
	s_waitcnt lgkmcnt(0)
	s_barrier

; DI unsigned xb_ld(unsigned* p)              { return __hip_atomic_load(p, __ATOMIC_RELAXED, __HIP_MEMORY_SCOPE_AGENT); }
; DI unsigned xb_add(unsigned* p, unsigned v) { return __hip_atomic_fetch_add(p, v, __ATOMIC_RELAXED, __HIP_MEMORY_SCOPE_AGENT); }
; #define XB_SPIN(cond, bar) do { unsigned _sp = 0; while (cond) { __builtin_amdgcn_s_sleep(1); \
;     if ((++_sp & 255u) == 0u) { if (xb_ld(&(bar)[XB_TMO])) break; if (_sp > XB_SPIN_CAP) { atomicAdd(&(bar)[XB_TMO], 1u); break; } } } } while (0)
; DI void xcd_barrier(const XcdBarrier& b) {
;     asm volatile("s_waitcnt vmcnt(0)" ::: "memory");
;     __syncthreads();
;     if (threadIdx.x == 0) {
;         unsigned* bar = b.bar;
;         __builtin_amdgcn_s_waitcnt(0);
;         unsigned nloc = b.st[0], nx = b.st[1];
;         if (nloc == 0u) { xcd_barrier_complete(bar, b.x, nloc, nx); b.st[0] = nloc; b.st[1] = nx; }
;         const unsigned old = xb_add(&bar[XB_XSUB(b.x)], 1u);
;         const unsigned gen = old / nloc;
;         if (old + 1u == (gen + 1u) * nloc) {
;             __builtin_amdgcn_fence(__ATOMIC_RELEASE, "agent");
;             asm volatile("s_waitcnt vmcnt(0)" ::: "memory");
;             const unsigned og = xb_add(&bar[XB_TOP], 1u);
;             const unsigned tg = og / nx;
;             if (og + 1u == (tg + 1u) * nx) xb_add(&bar[XB_TOPGEN], 1u);
;             else XB_SPIN(xb_ld(&bar[XB_TOPGEN]) == tg, bar);
;             __builtin_amdgcn_fence(__ATOMIC_ACQUIRE, "agent");
;             xb_add(&bar[XB_XGEN(b.x)], 1u);
;             asm volatile("s_waitcnt vmcnt(0)" ::: "memory");
.LBB0_345:
	s_cmp_gt_i32 s85, 2
	s_cselect_b64 s[0:1], -1, 0
	s_and_b64 s[4:5], s[12:13], s[0:1]
	s_andn2_b64 vcc, exec, s[4:5]
	s_cbranch_vccnz .LBB0_399
	s_waitcnt vmcnt(0) lgkmcnt(0)
	s_barrier
	v_readlane_b32 s3, v254, 3
	s_nop 3
	s_cmp_lg_u32 s3, 1
	s_cbranch_scc1 .Lmb2_notw1
	buffer_inv sc1
	s_waitcnt vmcnt(0)
	s_branch .Lmb2_end
.Lmb2_notw1:
	s_cmp_lg_u32 s3, 0
	s_cbranch_scc1 .Lmb2_end
	s_mov_b64 s[8:9], exec
	s_mov_b64 exec, 1
	v_mov_b32_e32 v0, 0x20100
	ds_read2_b32 v[2:3], v0 offset1:1
	s_add_u32 s10, s88, 0x3600
	s_addc_u32 s11, s89, 0
	s_lshl_b32 s22, s92, 8
	s_addk_i32 s22, 0x1400
	v_mov_b32_e32 v0, s22
	v_mov_b32_e32 v1, 1
	global_atomic_add v4, v0, v1, s[10:11] sc0
	s_waitcnt lgkmcnt(0)
	v_readfirstlane_b32 s12, v2
	v_readfirstlane_b32 s13, v3
	s_mul_i32 s12, s12, 2
	s_mul_i32 s13, s13, 2
	s_mov_b32 s23, 0
	s_waitcnt vmcnt(0)
	v_readfirstlane_b32 s3, v4
	s_add_i32 s3, s3, 1
	s_cmp_lg_u32 s3, s12
	s_cbranch_scc1 .Lmb2_wait
	buffer_wbl2 sc1
	s_waitcnt vmcnt(0)
	v_mov_b32_e32 v0, 0x3400
	global_atomic_add v4, v0, v1, s[10:11] sc0
	s_waitcnt vmcnt(0)
	v_readfirstlane_b32 s3, v4
	s_add_i32 s3, s3, 1
	s_cmp_lg_u32 s3, s13
	s_cbranch_scc1 .Lmb2_wait
	v_mov_b32_e32 v0, 0x2400
	global_atomic_add v0, v1, s[10:11]
	global_atomic_add v0, v1, s[10:11] offset:256
	global_atomic_add v0, v1, s[10:11] offset:512
	global_atomic_add v0, v1, s[10:11] offset:768
	global_atomic_add v0, v1, s[10:11] offset:1024
	global_atomic_add v0, v1, s[10:11] offset:1280
	global_atomic_add v0, v1, s[10:11] offset:1536
	global_atomic_add v0, v1, s[10:11] offset:1792
	global_atomic_add v0, v1, s[10:11] offset:2048
	global_atomic_add v0, v1, s[10:11] offset:2304
	global_atomic_add v0, v1, s[10:11] offset:2560
	global_atomic_add v0, v1, s[10:11] offset:2816
	global_atomic_add v0, v1, s[10:11] offset:3072
	global_atomic_add v0, v1, s[10:11] offset:3328
	global_atomic_add v0, v1, s[10:11] offset:3584
	global_atomic_add v0, v1, s[10:11] offset:3840
	s_branch .Lmb2_done

; DI unsigned xb_ld(unsigned* p)              { return __hip_atomic_load(p, __ATOMIC_RELAXED, __HIP_MEMORY_SCOPE_AGENT); }
; DI unsigned xb_add(unsigned* p, unsigned v) { return __hip_atomic_fetch_add(p, v, __ATOMIC_RELAXED, __HIP_MEMORY_SCOPE_AGENT); }
; #define XB_SPIN(cond, bar) do { unsigned _sp = 0; while (cond) { __builtin_amdgcn_s_sleep(1); \
;     if ((++_sp & 255u) == 0u) { if (xb_ld(&(bar)[XB_TMO])) break; if (_sp > XB_SPIN_CAP) { atomicAdd(&(bar)[XB_TMO], 1u); break; } } } } while (0)
; DI void xcd_barrier(const XcdBarrier& b) {
;     asm volatile("s_waitcnt vmcnt(0)" ::: "memory");
;     __syncthreads();
;     if (threadIdx.x == 0) {
;         unsigned* bar = b.bar;
;         __builtin_amdgcn_s_waitcnt(0);
;         unsigned nloc = b.st[0], nx = b.st[1];
;         if (nloc == 0u) { xcd_barrier_complete(bar, b.x, nloc, nx); b.st[0] = nloc; b.st[1] = nx; }
;         const unsigned old = xb_add(&bar[XB_XSUB(b.x)], 1u);
;         const unsigned gen = old / nloc;
;         if (old + 1u == (gen + 1u) * nloc) {
;             __builtin_amdgcn_fence(__ATOMIC_RELEASE, "agent");
;             asm volatile("s_waitcnt vmcnt(0)" ::: "memory");
;             const unsigned og = xb_add(&bar[XB_TOP], 1u);
;             const unsigned tg = og / nx;
;             if (og + 1u == (tg + 1u) * nx) xb_add(&bar[XB_TOPGEN], 1u);
;             else XB_SPIN(xb_ld(&bar[XB_TOPGEN]) == tg, bar);
;             __builtin_amdgcn_fence(__ATOMIC_ACQUIRE, "agent");
;             xb_add(&bar[XB_XGEN(b.x)], 1u);
;             asm volatile("s_waitcnt vmcnt(0)" ::: "memory");
.LBB0_536:
	s_cmp_gt_i32 s85, 4
	s_cselect_b64 s[0:1], -1, 0
	s_and_b64 s[4:5], s[10:11], s[0:1]
	s_andn2_b64 vcc, exec, s[4:5]
	s_cbranch_vccnz .LBB0_590
	s_waitcnt vmcnt(0) lgkmcnt(0)
	s_barrier
	v_readlane_b32 s3, v254, 3
	s_nop 3
	s_cmp_lg_u32 s3, 1
	s_cbranch_scc1 .Lmb4_notw1
	buffer_inv sc1
	s_waitcnt vmcnt(0)
	s_branch .Lmb4_end
.Lmb4_notw1:
	s_cmp_lg_u32 s3, 0
	s_cbranch_scc1 .Lmb4_end
	s_mov_b64 s[8:9], exec
	s_mov_b64 exec, 1
	v_mov_b32_e32 v0, 0x20100
	ds_read2_b32 v[2:3], v0 offset1:1
	s_add_u32 s10, s88, 0x3600
	s_addc_u32 s11, s89, 0
	s_lshl_b32 s22, s92, 8
	s_addk_i32 s22, 0x1400
	v_mov_b32_e32 v0, s22
	v_mov_b32_e32 v1, 1
	global_atomic_add v4, v0, v1, s[10:11] sc0
	s_waitcnt lgkmcnt(0)
	v_readfirstlane_b32 s12, v2
	v_readfirstlane_b32 s13, v3
	s_mul_i32 s12, s12, 3
	s_mul_i32 s13, s13, 3
	s_mov_b32 s23, 0
	s_waitcnt vmcnt(0)
	v_readfirstlane_b32 s3, v4
	s_add_i32 s3, s3, 1
	s_cmp_lg_u32 s3, s12
	s_cbranch_scc1 .Lmb4_wait
	buffer_wbl2 sc1
	s_waitcnt vmcnt(0)
	v_mov_b32_e32 v0, 0x3400
	global_atomic_add v4, v0, v1, s[10:11] sc0
	s_waitcnt vmcnt(0)
	v_readfirstlane_b32 s3, v4
	s_add_i32 s3, s3, 1
	s_cmp_lg_u32 s3, s13
	s_cbranch_scc1 .Lmb4_wait
	v_mov_b32_e32 v0, 0x2400
	global_atomic_add v0, v1, s[10:11]
	global_atomic_add v0, v1, s[10:11] offset:256
	global_atomic_add v0, v1, s[10:11] offset:512
	global_atomic_add v0, v1, s[10:11] offset:768
	global_atomic_add v0, v1, s[10:11] offset:1024
	global_atomic_add v0, v1, s[10:11] offset:1280
	global_atomic_add v0, v1, s[10:11] offset:1536
	global_atomic_add v0, v1, s[10:11] offset:1792
	global_atomic_add v0, v1, s[10:11] offset:2048
	global_atomic_add v0, v1, s[10:11] offset:2304
	global_atomic_add v0, v1, s[10:11] offset:2560
	global_atomic_add v0, v1, s[10:11] offset:2816
	global_atomic_add v0, v1, s[10:11] offset:3072
	global_atomic_add v0, v1, s[10:11] offset:3328
	global_atomic_add v0, v1, s[10:11] offset:3584
	global_atomic_add v0, v1, s[10:11] offset:3840
	s_branch .Lmb4_done

; DI unsigned xb_ld(unsigned* p)              { return __hip_atomic_load(p, __ATOMIC_RELAXED, __HIP_MEMORY_SCOPE_AGENT); }
; DI unsigned xb_add(unsigned* p, unsigned v) { return __hip_atomic_fetch_add(p, v, __ATOMIC_RELAXED, __HIP_MEMORY_SCOPE_AGENT); }
; #define XB_SPIN(cond, bar) do { unsigned _sp = 0; while (cond) { __builtin_amdgcn_s_sleep(1); \
;     if ((++_sp & 255u) == 0u) { if (xb_ld(&(bar)[XB_TMO])) break; if (_sp > XB_SPIN_CAP) { atomicAdd(&(bar)[XB_TMO], 1u); break; } } } } while (0)
; DI void xcd_barrier(const XcdBarrier& b) {
;     asm volatile("s_waitcnt vmcnt(0)" ::: "memory");
;     __syncthreads();
;     if (threadIdx.x == 0) {
;         unsigned* bar = b.bar;
;         __builtin_amdgcn_s_waitcnt(0);
;         unsigned nloc = b.st[0], nx = b.st[1];
;         if (nloc == 0u) { xcd_barrier_complete(bar, b.x, nloc, nx); b.st[0] = nloc; b.st[1] = nx; }
;         const unsigned old = xb_add(&bar[XB_XSUB(b.x)], 1u);
;         const unsigned gen = old / nloc;
;         if (old + 1u == (gen + 1u) * nloc) {
;             __builtin_amdgcn_fence(__ATOMIC_RELEASE, "agent");
;             asm volatile("s_waitcnt vmcnt(0)" ::: "memory");
;             const unsigned og = xb_add(&bar[XB_TOP], 1u);
;             const unsigned tg = og / nx;
;             if (og + 1u == (tg + 1u) * nx) xb_add(&bar[XB_TOPGEN], 1u);
;             else XB_SPIN(xb_ld(&bar[XB_TOPGEN]) == tg, bar);
;             __builtin_amdgcn_fence(__ATOMIC_ACQUIRE, "agent");
;             xb_add(&bar[XB_XGEN(b.x)], 1u);
;             asm volatile("s_waitcnt vmcnt(0)" ::: "memory");
.LBB0_625:
	s_cmp_gt_i32 s85, 5
	s_cselect_b64 s[4:5], -1, 0
	s_and_b64 s[0:1], s[14:15], s[4:5]
	s_andn2_b64 vcc, exec, s[0:1]
	s_cbranch_vccnz .LBB0_679
	s_waitcnt vmcnt(0) lgkmcnt(0)
	s_barrier
	v_readlane_b32 s3, v254, 3
	s_nop 3
	s_cmp_lg_u32 s3, 1
	s_cbranch_scc1 .Lmb5_notw1
	buffer_inv sc1
	s_waitcnt vmcnt(0)
	s_branch .Lmb5_end
.Lmb5_notw1:
	s_cmp_lg_u32 s3, 0
	s_cbranch_scc1 .Lmb5_end
	s_mov_b64 s[8:9], exec
	s_mov_b64 exec, 1
	v_mov_b32_e32 v0, 0x20100
	ds_read2_b32 v[2:3], v0 offset1:1
	s_add_u32 s10, s88, 0x3600
	s_addc_u32 s11, s89, 0
	s_lshl_b32 s22, s92, 8
	s_addk_i32 s22, 0x1400
	v_mov_b32_e32 v0, s22
	v_mov_b32_e32 v1, 1
	global_atomic_add v4, v0, v1, s[10:11] sc0
	s_waitcnt lgkmcnt(0)
	v_readfirstlane_b32 s12, v2
	v_readfirstlane_b32 s13, v3
	s_mul_i32 s12, s12, 4
	s_mul_i32 s13, s13, 4
	s_mov_b32 s23, 0
	s_waitcnt vmcnt(0)
	v_readfirstlane_b32 s3, v4
	s_add_i32 s3, s3, 1
	s_cmp_lg_u32 s3, s12
	s_cbranch_scc1 .Lmb5_wait
	buffer_wbl2 sc1
	s_waitcnt vmcnt(0)
	v_mov_b32_e32 v0, 0x3400
	global_atomic_add v4, v0, v1, s[10:11] sc0
	s_waitcnt vmcnt(0)
	v_readfirstlane_b32 s3, v4
	s_add_i32 s3, s3, 1
	s_cmp_lg_u32 s3, s13
	s_cbranch_scc1 .Lmb5_wait
	v_mov_b32_e32 v0, 0x2400
	global_atomic_add v0, v1, s[10:11]
	global_atomic_add v0, v1, s[10:11] offset:256
	global_atomic_add v0, v1, s[10:11] offset:512
	global_atomic_add v0, v1, s[10:11] offset:768
	global_atomic_add v0, v1, s[10:11] offset:1024
	global_atomic_add v0, v1, s[10:11] offset:1280
	global_atomic_add v0, v1, s[10:11] offset:1536
	global_atomic_add v0, v1, s[10:11] offset:1792
	global_atomic_add v0, v1, s[10:11] offset:2048
	global_atomic_add v0, v1, s[10:11] offset:2304
	global_atomic_add v0, v1, s[10:11] offset:2560
	global_atomic_add v0, v1, s[10:11] offset:2816
	global_atomic_add v0, v1, s[10:11] offset:3072
	global_atomic_add v0, v1, s[10:11] offset:3328
	global_atomic_add v0, v1, s[10:11] offset:3584
	global_atomic_add v0, v1, s[10:11] offset:3840
	s_branch .Lmb5_done

; DI unsigned xb_ld(unsigned* p)              { return __hip_atomic_load(p, __ATOMIC_RELAXED, __HIP_MEMORY_SCOPE_AGENT); }
; DI unsigned xb_add(unsigned* p, unsigned v) { return __hip_atomic_fetch_add(p, v, __ATOMIC_RELAXED, __HIP_MEMORY_SCOPE_AGENT); }
; #define XB_SPIN(cond, bar) do { unsigned _sp = 0; while (cond) { __builtin_amdgcn_s_sleep(1); \
;     if ((++_sp & 255u) == 0u) { if (xb_ld(&(bar)[XB_TMO])) break; if (_sp > XB_SPIN_CAP) { atomicAdd(&(bar)[XB_TMO], 1u); break; } } } } while (0)
; DI void xcd_barrier(const XcdBarrier& b) {
;     asm volatile("s_waitcnt vmcnt(0)" ::: "memory");
;     __syncthreads();
;     if (threadIdx.x == 0) {
;         unsigned* bar = b.bar;
;         __builtin_amdgcn_s_waitcnt(0);
;         unsigned nloc = b.st[0], nx = b.st[1];
;         if (nloc == 0u) { xcd_barrier_complete(bar, b.x, nloc, nx); b.st[0] = nloc; b.st[1] = nx; }
;         const unsigned old = xb_add(&bar[XB_XSUB(b.x)], 1u);
;         const unsigned gen = old / nloc;
;         if (old + 1u == (gen + 1u) * nloc) {
;             __builtin_amdgcn_fence(__ATOMIC_RELEASE, "agent");
;             asm volatile("s_waitcnt vmcnt(0)" ::: "memory");
;             const unsigned og = xb_add(&bar[XB_TOP], 1u);
;             const unsigned tg = og / nx;
;             if (og + 1u == (tg + 1u) * nx) xb_add(&bar[XB_TOPGEN], 1u);
;             else XB_SPIN(xb_ld(&bar[XB_TOPGEN]) == tg, bar);
;             __builtin_amdgcn_fence(__ATOMIC_ACQUIRE, "agent");
;             xb_add(&bar[XB_XGEN(b.x)], 1u);
;             asm volatile("s_waitcnt vmcnt(0)" ::: "memory");
.LBB0_722:
	s_cmp_gt_i32 s85, 6
	s_cselect_b64 s[4:5], -1, 0
	s_and_b64 s[6:7], s[8:9], s[4:5]
	s_andn2_b64 vcc, exec, s[6:7]
	s_cbranch_vccnz .LBB0_776
	s_waitcnt vmcnt(0) lgkmcnt(0)
	s_barrier
	v_readlane_b32 s3, v254, 3
	s_nop 3
	s_cmp_lg_u32 s3, 1
	s_cbranch_scc1 .Lmb6_notw1
	buffer_inv sc1
	s_waitcnt vmcnt(0)
	s_branch .Lmb6_end
.Lmb6_notw1:
	s_cmp_lg_u32 s3, 0
	s_cbranch_scc1 .Lmb6_end
	s_mov_b64 s[8:9], exec
	s_mov_b64 exec, 1
	v_mov_b32_e32 v0, 0x20100
	ds_read2_b32 v[2:3], v0 offset1:1
	s_add_u32 s10, s88, 0x3600
	s_addc_u32 s11, s89, 0
	s_lshl_b32 s22, s92, 8
	s_addk_i32 s22, 0x1400
	v_mov_b32_e32 v0, s22
	v_mov_b32_e32 v1, 1
	global_atomic_add v4, v0, v1, s[10:11] sc0
	s_waitcnt lgkmcnt(0)
	v_readfirstlane_b32 s12, v2
	v_readfirstlane_b32 s13, v3
	s_mul_i32 s12, s12, 5
	s_mul_i32 s13, s13, 5
	s_mov_b32 s23, 0
	s_waitcnt vmcnt(0)
	v_readfirstlane_b32 s3, v4
	s_add_i32 s3, s3, 1
	s_cmp_lg_u32 s3, s12
	s_cbranch_scc1 .Lmb6_wait
	buffer_wbl2 sc1
	s_waitcnt vmcnt(0)
	v_mov_b32_e32 v0, 0x3400
	global_atomic_add v4, v0, v1, s[10:11] sc0
	s_waitcnt vmcnt(0)
	v_readfirstlane_b32 s3, v4
	s_add_i32 s3, s3, 1
	s_cmp_lg_u32 s3, s13
	s_cbranch_scc1 .Lmb6_wait
	v_mov_b32_e32 v0, 0x2400
	global_atomic_add v0, v1, s[10:11]
	global_atomic_add v0, v1, s[10:11] offset:256
	global_atomic_add v0, v1, s[10:11] offset:512
	global_atomic_add v0, v1, s[10:11] offset:768
	global_atomic_add v0, v1, s[10:11] offset:1024
	global_atomic_add v0, v1, s[10:11] offset:1280
	global_atomic_add v0, v1, s[10:11] offset:1536
	global_atomic_add v0, v1, s[10:11] offset:1792
	global_atomic_add v0, v1, s[10:11] offset:2048
	global_atomic_add v0, v1, s[10:11] offset:2304
	global_atomic_add v0, v1, s[10:11] offset:2560
	global_atomic_add v0, v1, s[10:11] offset:2816
	global_atomic_add v0, v1, s[10:11] offset:3072
	global_atomic_add v0, v1, s[10:11] offset:3328
	global_atomic_add v0, v1, s[10:11] offset:3584
	global_atomic_add v0, v1, s[10:11] offset:3840
	s_branch .Lmb6_done

; DI unsigned xb_ld(unsigned* p)              { return __hip_atomic_load(p, __ATOMIC_RELAXED, __HIP_MEMORY_SCOPE_AGENT); }
; DI unsigned xb_add(unsigned* p, unsigned v) { return __hip_atomic_fetch_add(p, v, __ATOMIC_RELAXED, __HIP_MEMORY_SCOPE_AGENT); }
; #define XB_SPIN(cond, bar) do { unsigned _sp = 0; while (cond) { __builtin_amdgcn_s_sleep(1); \
;     if ((++_sp & 255u) == 0u) { if (xb_ld(&(bar)[XB_TMO])) break; if (_sp > XB_SPIN_CAP) { atomicAdd(&(bar)[XB_TMO], 1u); break; } } } } while (0)
; DI void xcd_barrier(const XcdBarrier& b) {
;     asm volatile("s_waitcnt vmcnt(0)" ::: "memory");
;     __syncthreads();
;     if (threadIdx.x == 0) {
;         unsigned* bar = b.bar;
;         __builtin_amdgcn_s_waitcnt(0);
;         unsigned nloc = b.st[0], nx = b.st[1];
;         if (nloc == 0u) { xcd_barrier_complete(bar, b.x, nloc, nx); b.st[0] = nloc; b.st[1] = nx; }
;         const unsigned old = xb_add(&bar[XB_XSUB(b.x)], 1u);
;         const unsigned gen = old / nloc;
;         if (old + 1u == (gen + 1u) * nloc) {
;             __builtin_amdgcn_fence(__ATOMIC_RELEASE, "agent");
;             asm volatile("s_waitcnt vmcnt(0)" ::: "memory");
;             const unsigned og = xb_add(&bar[XB_TOP], 1u);
;             const unsigned tg = og / nx;
;             if (og + 1u == (tg + 1u) * nx) xb_add(&bar[XB_TOPGEN], 1u);
;             else XB_SPIN(xb_ld(&bar[XB_TOPGEN]) == tg, bar);
;             __builtin_amdgcn_fence(__ATOMIC_ACQUIRE, "agent");
;             xb_add(&bar[XB_XGEN(b.x)], 1u);
;             asm volatile("s_waitcnt vmcnt(0)" ::: "memory");
.LBB0_931:
	s_cmp_gt_i32 s85, 7
	s_cselect_b64 s[0:1], -1, 0
	s_and_b64 s[4:5], s[12:13], s[0:1]
	s_andn2_b64 vcc, exec, s[4:5]
	s_cbranch_vccnz .LBB0_985
	s_waitcnt vmcnt(0) lgkmcnt(0)
	s_barrier
	v_readlane_b32 s3, v254, 3
	s_nop 3
	s_cmp_lg_u32 s3, 1
	s_cbranch_scc1 .Lmb7_notw1
	buffer_inv sc1
	s_waitcnt vmcnt(0)
	s_branch .Lmb7_end
.Lmb7_notw1:
	s_cmp_lg_u32 s3, 0
	s_cbranch_scc1 .Lmb7_end
	s_mov_b64 s[8:9], exec
	s_mov_b64 exec, 1
	v_mov_b32_e32 v0, 0x20100
	ds_read2_b32 v[2:3], v0 offset1:1
	s_add_u32 s10, s88, 0x3600
	s_addc_u32 s11, s89, 0
	s_lshl_b32 s22, s92, 8
	s_addk_i32 s22, 0x1400
	v_mov_b32_e32 v0, s22
	v_mov_b32_e32 v1, 1
	global_atomic_add v4, v0, v1, s[10:11] sc0
	s_waitcnt lgkmcnt(0)
	v_readfirstlane_b32 s12, v2
	v_readfirstlane_b32 s13, v3
	s_mul_i32 s12, s12, 6
	s_mul_i32 s13, s13, 6
	s_mov_b32 s23, 0
	s_waitcnt vmcnt(0)
	v_readfirstlane_b32 s3, v4
	s_add_i32 s3, s3, 1
	s_cmp_lg_u32 s3, s12
	s_cbranch_scc1 .Lmb7_wait
	buffer_wbl2 sc1
	s_waitcnt vmcnt(0)
	v_mov_b32_e32 v0, 0x3400
	global_atomic_add v4, v0, v1, s[10:11] sc0
	s_waitcnt vmcnt(0)
	v_readfirstlane_b32 s3, v4
	s_add_i32 s3, s3, 1
	s_cmp_lg_u32 s3, s13
	s_cbranch_scc1 .Lmb7_wait
	v_mov_b32_e32 v0, 0x2400
	global_atomic_add v0, v1, s[10:11]
	global_atomic_add v0, v1, s[10:11] offset:256
	global_atomic_add v0, v1, s[10:11] offset:512
	global_atomic_add v0, v1, s[10:11] offset:768
	global_atomic_add v0, v1, s[10:11] offset:1024
	global_atomic_add v0, v1, s[10:11] offset:1280
	global_atomic_add v0, v1, s[10:11] offset:1536
	global_atomic_add v0, v1, s[10:11] offset:1792
	global_atomic_add v0, v1, s[10:11] offset:2048
	global_atomic_add v0, v1, s[10:11] offset:2304
	global_atomic_add v0, v1, s[10:11] offset:2560
	global_atomic_add v0, v1, s[10:11] offset:2816
	global_atomic_add v0, v1, s[10:11] offset:3072
	global_atomic_add v0, v1, s[10:11] offset:3328
	global_atomic_add v0, v1, s[10:11] offset:3584
	global_atomic_add v0, v1, s[10:11] offset:3840
	s_branch .Lmb7_done

; DI unsigned xb_ld(unsigned* p)              { return __hip_atomic_load(p, __ATOMIC_RELAXED, __HIP_MEMORY_SCOPE_AGENT); }
; DI unsigned xb_add(unsigned* p, unsigned v) { return __hip_atomic_fetch_add(p, v, __ATOMIC_RELAXED, __HIP_MEMORY_SCOPE_AGENT); }
; #define XB_SPIN(cond, bar) do { unsigned _sp = 0; while (cond) { __builtin_amdgcn_s_sleep(1); \
;     if ((++_sp & 255u) == 0u) { if (xb_ld(&(bar)[XB_TMO])) break; if (_sp > XB_SPIN_CAP) { atomicAdd(&(bar)[XB_TMO], 1u); break; } } } } while (0)
; DI void xcd_barrier(const XcdBarrier& b) {
;     asm volatile("s_waitcnt vmcnt(0)" ::: "memory");
;     __syncthreads();
;     if (threadIdx.x == 0) {
;         unsigned* bar = b.bar;
;         __builtin_amdgcn_s_waitcnt(0);
;         unsigned nloc = b.st[0], nx = b.st[1];
;         if (nloc == 0u) { xcd_barrier_complete(bar, b.x, nloc, nx); b.st[0] = nloc; b.st[1] = nx; }
;         const unsigned old = xb_add(&bar[XB_XSUB(b.x)], 1u);
;         const unsigned gen = old / nloc;
;         if (old + 1u == (gen + 1u) * nloc) {
;             __builtin_amdgcn_fence(__ATOMIC_RELEASE, "agent");
;             asm volatile("s_waitcnt vmcnt(0)" ::: "memory");
;             const unsigned og = xb_add(&bar[XB_TOP], 1u);
;             const unsigned tg = og / nx;
;             if (og + 1u == (tg + 1u) * nx) xb_add(&bar[XB_TOPGEN], 1u);
;             else XB_SPIN(xb_ld(&bar[XB_TOPGEN]) == tg, bar);
;             __builtin_amdgcn_fence(__ATOMIC_ACQUIRE, "agent");
;             xb_add(&bar[XB_XGEN(b.x)], 1u);
;             asm volatile("s_waitcnt vmcnt(0)" ::: "memory");
.LBB0_993:
	s_cmp_gt_i32 s85, 8
	s_cselect_b64 s[4:5], -1, 0
	s_and_b64 s[0:1], s[0:1], s[4:5]
	s_andn2_b64 vcc, exec, s[0:1]
	s_cbranch_vccnz .LBB0_1047
	s_waitcnt vmcnt(0) lgkmcnt(0)
	s_barrier
	v_readlane_b32 s3, v254, 3
	s_nop 3
	s_cmp_lg_u32 s3, 1
	s_cbranch_scc1 .Lmb8_notw1
	buffer_inv sc1
	s_waitcnt vmcnt(0)
	s_branch .Lmb8_end
.Lmb8_notw1:
	s_cmp_lg_u32 s3, 0
	s_cbranch_scc1 .Lmb8_end
	s_mov_b64 s[8:9], exec
	s_mov_b64 exec, 1
	v_mov_b32_e32 v0, 0x20100
	ds_read2_b32 v[2:3], v0 offset1:1
	s_add_u32 s10, s88, 0x3600
	s_addc_u32 s11, s89, 0
	s_lshl_b32 s22, s92, 8
	s_addk_i32 s22, 0x1400
	v_mov_b32_e32 v0, s22
	v_mov_b32_e32 v1, 1
	global_atomic_add v4, v0, v1, s[10:11] sc0
	s_waitcnt lgkmcnt(0)
	v_readfirstlane_b32 s12, v2
	v_readfirstlane_b32 s13, v3
	s_mul_i32 s12, s12, 7
	s_mul_i32 s13, s13, 7
	s_mov_b32 s23, 0
	s_waitcnt vmcnt(0)
	v_readfirstlane_b32 s3, v4
	s_add_i32 s3, s3, 1
	s_cmp_lg_u32 s3, s12
	s_cbranch_scc1 .Lmb8_wait
	buffer_wbl2 sc1
	s_waitcnt vmcnt(0)
	v_mov_b32_e32 v0, 0x3400
	global_atomic_add v4, v0, v1, s[10:11] sc0
	s_waitcnt vmcnt(0)
	v_readfirstlane_b32 s3, v4
	s_add_i32 s3, s3, 1
	s_cmp_lg_u32 s3, s13
	s_cbranch_scc1 .Lmb8_wait
	v_mov_b32_e32 v0, 0x2400
	global_atomic_add v0, v1, s[10:11]
	global_atomic_add v0, v1, s[10:11] offset:256
	global_atomic_add v0, v1, s[10:11] offset:512
	global_atomic_add v0, v1, s[10:11] offset:768
	global_atomic_add v0, v1, s[10:11] offset:1024
	global_atomic_add v0, v1, s[10:11] offset:1280
	global_atomic_add v0, v1, s[10:11] offset:1536
	global_atomic_add v0, v1, s[10:11] offset:1792
	global_atomic_add v0, v1, s[10:11] offset:2048
	global_atomic_add v0, v1, s[10:11] offset:2304
	global_atomic_add v0, v1, s[10:11] offset:2560
	global_atomic_add v0, v1, s[10:11] offset:2816
	global_atomic_add v0, v1, s[10:11] offset:3072
	global_atomic_add v0, v1, s[10:11] offset:3328
	global_atomic_add v0, v1, s[10:11] offset:3584
	global_atomic_add v0, v1, s[10:11] offset:3840
	s_branch .Lmb8_done

; DI unsigned xb_ld(unsigned* p)              { return __hip_atomic_load(p, __ATOMIC_RELAXED, __HIP_MEMORY_SCOPE_AGENT); }
; DI unsigned xb_add(unsigned* p, unsigned v) { return __hip_atomic_fetch_add(p, v, __ATOMIC_RELAXED, __HIP_MEMORY_SCOPE_AGENT); }
; #define XB_SPIN(cond, bar) do { unsigned _sp = 0; while (cond) { __builtin_amdgcn_s_sleep(1); \
;     if ((++_sp & 255u) == 0u) { if (xb_ld(&(bar)[XB_TMO])) break; if (_sp > XB_SPIN_CAP) { atomicAdd(&(bar)[XB_TMO], 1u); break; } } } } while (0)
; DI void xcd_barrier(const XcdBarrier& b) {
;     asm volatile("s_waitcnt vmcnt(0)" ::: "memory");
;     __syncthreads();
;     if (threadIdx.x == 0) {
;         unsigned* bar = b.bar;
;         __builtin_amdgcn_s_waitcnt(0);
;         unsigned nloc = b.st[0], nx = b.st[1];
;         if (nloc == 0u) { xcd_barrier_complete(bar, b.x, nloc, nx); b.st[0] = nloc; b.st[1] = nx; }
;         const unsigned old = xb_add(&bar[XB_XSUB(b.x)], 1u);
;         const unsigned gen = old / nloc;
;         if (old + 1u == (gen + 1u) * nloc) {
;             __builtin_amdgcn_fence(__ATOMIC_RELEASE, "agent");
;             asm volatile("s_waitcnt vmcnt(0)" ::: "memory");
;             const unsigned og = xb_add(&bar[XB_TOP], 1u);
;             const unsigned tg = og / nx;
;             if (og + 1u == (tg + 1u) * nx) xb_add(&bar[XB_TOPGEN], 1u);
;             else XB_SPIN(xb_ld(&bar[XB_TOPGEN]) == tg, bar);
;             __builtin_amdgcn_fence(__ATOMIC_ACQUIRE, "agent");
;             xb_add(&bar[XB_XGEN(b.x)], 1u);
;             asm volatile("s_waitcnt vmcnt(0)" ::: "memory");
.LBB0_1054:
	s_cmp_gt_i32 s85, 9
	s_cselect_b64 s[0:1], -1, 0
	s_and_b64 s[4:5], s[6:7], s[0:1]
	s_andn2_b64 vcc, exec, s[4:5]
	s_cbranch_vccnz .LBB0_1108
	s_waitcnt vmcnt(0) lgkmcnt(0)
	s_barrier
	v_readlane_b32 s3, v254, 3
	s_nop 3
	s_cmp_lg_u32 s3, 1
	s_cbranch_scc1 .Lmb9_notw1
	buffer_inv sc1
	s_waitcnt vmcnt(0)
	s_branch .Lmb9_end
.Lmb9_notw1:
	s_cmp_lg_u32 s3, 0
	s_cbranch_scc1 .Lmb9_end
	s_mov_b64 s[8:9], exec
	s_mov_b64 exec, 1
	v_mov_b32_e32 v0, 0x20100
	ds_read2_b32 v[2:3], v0 offset1:1
	s_add_u32 s10, s88, 0x3600
	s_addc_u32 s11, s89, 0
	s_lshl_b32 s22, s92, 8
	s_addk_i32 s22, 0x1400
	v_mov_b32_e32 v0, s22
	v_mov_b32_e32 v1, 1
	global_atomic_add v4, v0, v1, s[10:11] sc0
	s_waitcnt lgkmcnt(0)
	v_readfirstlane_b32 s12, v2
	v_readfirstlane_b32 s13, v3
	s_mul_i32 s12, s12, 8
	s_mul_i32 s13, s13, 8
	s_mov_b32 s23, 0
	s_waitcnt vmcnt(0)
	v_readfirstlane_b32 s3, v4
	s_add_i32 s3, s3, 1
	s_cmp_lg_u32 s3, s12
	s_cbranch_scc1 .Lmb9_wait
	buffer_wbl2 sc1
	s_waitcnt vmcnt(0)
	v_mov_b32_e32 v0, 0x3400
	global_atomic_add v4, v0, v1, s[10:11] sc0
	s_waitcnt vmcnt(0)
	v_readfirstlane_b32 s3, v4
	s_add_i32 s3, s3, 1
	s_cmp_lg_u32 s3, s13
	s_cbranch_scc1 .Lmb9_wait
	v_mov_b32_e32 v0, 0x2400
	global_atomic_add v0, v1, s[10:11]
	global_atomic_add v0, v1, s[10:11] offset:256
	global_atomic_add v0, v1, s[10:11] offset:512
	global_atomic_add v0, v1, s[10:11] offset:768
	global_atomic_add v0, v1, s[10:11] offset:1024
	global_atomic_add v0, v1, s[10:11] offset:1280
	global_atomic_add v0, v1, s[10:11] offset:1536
	global_atomic_add v0, v1, s[10:11] offset:1792
	global_atomic_add v0, v1, s[10:11] offset:2048
	global_atomic_add v0, v1, s[10:11] offset:2304
	global_atomic_add v0, v1, s[10:11] offset:2560
	global_atomic_add v0, v1, s[10:11] offset:2816
	global_atomic_add v0, v1, s[10:11] offset:3072
	global_atomic_add v0, v1, s[10:11] offset:3328
	global_atomic_add v0, v1, s[10:11] offset:3584
	global_atomic_add v0, v1, s[10:11] offset:3840
	s_branch .Lmb9_done

; DI unsigned xb_ld(unsigned* p)              { return __hip_atomic_load(p, __ATOMIC_RELAXED, __HIP_MEMORY_SCOPE_AGENT); }
; DI unsigned xb_add(unsigned* p, unsigned v) { return __hip_atomic_fetch_add(p, v, __ATOMIC_RELAXED, __HIP_MEMORY_SCOPE_AGENT); }
; #define XB_SPIN(cond, bar) do { unsigned _sp = 0; while (cond) { __builtin_amdgcn_s_sleep(1); \
;     if ((++_sp & 255u) == 0u) { if (xb_ld(&(bar)[XB_TMO])) break; if (_sp > XB_SPIN_CAP) { atomicAdd(&(bar)[XB_TMO], 1u); break; } } } } while (0)
; DI void xcd_barrier(const XcdBarrier& b) {
;     asm volatile("s_waitcnt vmcnt(0)" ::: "memory");
;     __syncthreads();
;     if (threadIdx.x == 0) {
;         unsigned* bar = b.bar;
;         __builtin_amdgcn_s_waitcnt(0);
;         unsigned nloc = b.st[0], nx = b.st[1];
;         if (nloc == 0u) { xcd_barrier_complete(bar, b.x, nloc, nx); b.st[0] = nloc; b.st[1] = nx; }
;         const unsigned old = xb_add(&bar[XB_XSUB(b.x)], 1u);
;         const unsigned gen = old / nloc;
;         if (old + 1u == (gen + 1u) * nloc) {
;             __builtin_amdgcn_fence(__ATOMIC_RELEASE, "agent");
;             asm volatile("s_waitcnt vmcnt(0)" ::: "memory");
;             const unsigned og = xb_add(&bar[XB_TOP], 1u);
;             const unsigned tg = og / nx;
;             if (og + 1u == (tg + 1u) * nx) xb_add(&bar[XB_TOPGEN], 1u);
;             else XB_SPIN(xb_ld(&bar[XB_TOPGEN]) == tg, bar);
;             __builtin_amdgcn_fence(__ATOMIC_ACQUIRE, "agent");
;             xb_add(&bar[XB_XGEN(b.x)], 1u);
;             asm volatile("s_waitcnt vmcnt(0)" ::: "memory");
.LBB0_1124:
	s_cmp_gt_i32 s85, 10
	s_cselect_b64 s[4:5], -1, 0
	s_and_b64 s[0:1], s[0:1], s[4:5]
	s_andn2_b64 vcc, exec, s[0:1]
	s_cbranch_vccnz .LBB0_1178
	s_waitcnt vmcnt(0) lgkmcnt(0)
	s_barrier
	v_readlane_b32 s3, v254, 3
	s_nop 3
	s_cmp_lg_u32 s3, 1
	s_cbranch_scc1 .Lmb10_notw1
	buffer_inv sc1
	s_waitcnt vmcnt(0)
	s_branch .Lmb10_end
.Lmb10_notw1:
	s_cmp_lg_u32 s3, 0
	s_cbranch_scc1 .Lmb10_end
	s_mov_b64 s[8:9], exec
	s_mov_b64 exec, 1
	v_mov_b32_e32 v0, 0x20100
	ds_read2_b32 v[2:3], v0 offset1:1
	s_add_u32 s10, s88, 0x3600
	s_addc_u32 s11, s89, 0
	s_lshl_b32 s22, s92, 8
	s_addk_i32 s22, 0x1400
	v_mov_b32_e32 v0, s22
	v_mov_b32_e32 v1, 1
	global_atomic_add v4, v0, v1, s[10:11] sc0
	s_waitcnt lgkmcnt(0)
	v_readfirstlane_b32 s12, v2
	v_readfirstlane_b32 s13, v3
	s_mul_i32 s12, s12, 9
	s_mul_i32 s13, s13, 9
	s_mov_b32 s23, 0
	s_waitcnt vmcnt(0)
	v_readfirstlane_b32 s3, v4
	s_add_i32 s3, s3, 1
	s_cmp_lg_u32 s3, s12
	s_cbranch_scc1 .Lmb10_wait
	buffer_wbl2 sc1
	s_waitcnt vmcnt(0)
	v_mov_b32_e32 v0, 0x3400
	global_atomic_add v4, v0, v1, s[10:11] sc0
	s_waitcnt vmcnt(0)
	v_readfirstlane_b32 s3, v4
	s_add_i32 s3, s3, 1
	s_cmp_lg_u32 s3, s13
	s_cbranch_scc1 .Lmb10_wait
	v_mov_b32_e32 v0, 0x2400
	global_atomic_add v0, v1, s[10:11]
	global_atomic_add v0, v1, s[10:11] offset:256
	global_atomic_add v0, v1, s[10:11] offset:512
	global_atomic_add v0, v1, s[10:11] offset:768
	global_atomic_add v0, v1, s[10:11] offset:1024
	global_atomic_add v0, v1, s[10:11] offset:1280
	global_atomic_add v0, v1, s[10:11] offset:1536
	global_atomic_add v0, v1, s[10:11] offset:1792
	global_atomic_add v0, v1, s[10:11] offset:2048
	global_atomic_add v0, v1, s[10:11] offset:2304
	global_atomic_add v0, v1, s[10:11] offset:2560
	global_atomic_add v0, v1, s[10:11] offset:2816
	global_atomic_add v0, v1, s[10:11] offset:3072
	global_atomic_add v0, v1, s[10:11] offset:3328
	global_atomic_add v0, v1, s[10:11] offset:3584
	global_atomic_add v0, v1, s[10:11] offset:3840
	s_branch .Lmb10_done

.Lmb10_spin:
	global_load_dword v4, v0, s[10:11] sc1
	s_waitcnt vmcnt(0)
	v_readfirstlane_b32 s3, v4
	s_cmp_gt_u32 s3, 8
	s_cbranch_scc1 .Lmb10_got
	s_add_i32 s23, s23, 1
	s_cmp_lt_u32 s23, 0x40000
	s_cbranch_scc0 .Lmb10_got
	s_sleep 1
	s_branch .Lmb10_spin

;     DI void fused(f32x4 (&acc)[2][2][4][2], const Unit& u, int wr, int wc, int fr, int fq, LAS unsigned char* lds, int wid, int lane) const {
;     ...
;         asm volatile("s_waitcnt vmcnt(0)" ::: "memory");
;         __syncthreads();
;         if (tid == 0) {
;             __builtin_amdgcn_fence(__ATOMIC_RELEASE, "agent");
;             __hip_atomic_fetch_add(cnt + 64 * u.pm, 1u, __ATOMIC_RELAXED, __HIP_MEMORY_SCOPE_AGENT);
;             unsigned sp = 0;
.LBB0_1248:
	s_or_b64 exec, exec, s[6:7]
	s_waitcnt vmcnt(0)
	v_cmp_eq_u32_e32 vcc, 0, v2
	s_barrier
	s_and_saveexec_b64 s[6:7], vcc
	s_cbranch_execz .LBB0_1260
	s_lshl_b32 s8, s8, 6
	s_ashr_i32 s9, s8, 31
	s_lshl_b64 s[8:9], s[8:9], 2
	s_mov_b64 s[10:11], exec
	s_add_u32 s3, s82, s8
	s_addc_u32 s9, s83, s9
	v_mbcnt_lo_u32_b32 v3, s10, 0
	s_add_u32 s8, s3, 0xc6c00
	v_mbcnt_hi_u32_b32 v3, s11, v3
	s_addc_u32 s9, s9, 0
	v_cmp_eq_u32_e32 vcc, 0, v3
	s_nop 0
	s_waitcnt vmcnt(0)
	s_and_saveexec_b64 s[12:13], vcc
	s_cbranch_execz .LBB0_1251
	s_bcnt1_i32_b64 s3, s[10:11]
	v_mov_b32_e32 v3, 0
	v_mov_b32_e32 v4, s3
	global_atomic_add v3, v4, s[8:9]

;     DI void fused(f32x4 (&acc)[2][2][4][2], const Unit& u, int wr, int wc, int fr, int fq, LAS unsigned char* lds, int wid, int lane) const {
;     ...
;             while (__hip_atomic_load(cnt + 64 * u.pm, __ATOMIC_RELAXED, __HIP_MEMORY_SCOPE_AGENT) < 8u) { __builtin_amdgcn_s_sleep(1); if (++sp > (1u << 22)) break; }
;             __builtin_amdgcn_fence(__ATOMIC_ACQUIRE, "agent");
;         }
;         __syncthreads();
;         if (tid < 256) {
;             const float* pp = part + (size_t)(u.pm * 256 + tid) * 8;
;             float s = 0.f;
; #pragma unroll
;             for (int j = 0; j < 8; ++j) s += __hip_atomic_load(pp + j, __ATOMIC_RELAXED, __HIP_MEMORY_SCOPE_AGENT);
;             R[tid] = rsqrtf(s * (1.f / 2048.f) + EPS_);
;         }
.LBB0_1253:
	global_load_dword v4, v3, s[8:9] sc1
	s_mov_b64 s[10:11], -1
	s_waitcnt vmcnt(0)
	v_cmp_lt_u32_e32 vcc, 7, v4
	s_cbranch_vccnz .LBB0_1252
	s_sleep 1
	global_load_dword v4, v3, s[8:9] sc1
	s_waitcnt vmcnt(0)
	v_cmp_gt_u32_e32 vcc, 8, v4
	s_cbranch_vccz .LBB0_1252
	s_sleep 1
	global_load_dword v4, v3, s[8:9] sc1
	s_waitcnt vmcnt(0)
	v_cmp_gt_u32_e32 vcc, 8, v4
	s_cbranch_vccz .LBB0_1252
	s_sleep 1
	global_load_dword v4, v3, s[8:9] sc1
	s_waitcnt vmcnt(0)
	v_cmp_gt_u32_e32 vcc, 8, v4
	s_cbranch_vccz .LBB0_1252
	s_sleep 1
	global_load_dword v4, v3, s[8:9] sc1
	s_waitcnt vmcnt(0)
	v_cmp_gt_u32_e32 vcc, 8, v4
	s_cbranch_vccz .LBB0_1252
	s_add_i32 s3, s3, -5
	s_cmp_eq_u32 s3, 0
	s_cselect_b64 s[10:11], -1, 0
	s_sleep 1
	s_branch .LBB0_1252
.LBB0_1259:
	s_nop 0
.LBB0_1260:
	s_or_b64 exec, exec, s[6:7]
	s_barrier
	s_and_saveexec_b64 s[6:7], s[4:5]
	s_cbranch_execz .LBB0_1262
	v_lshlrev_b64 v[0:1], 5, v[0:1]
	v_lshl_add_u64 v[0:1], s[60:61], 0, v[0:1]
	global_load_dword v3, v[0:1], off sc1
	global_load_dword v4, v[0:1], off offset:4 sc1
	global_load_dword v5, v[0:1], off offset:8 sc1
	global_load_dword v6, v[0:1], off offset:12 sc1
	global_load_dword v7, v[0:1], off offset:16 sc1
	global_load_dword v8, v[0:1], off offset:20 sc1
	global_load_dword v9, v[0:1], off offset:24 sc1
	s_nop 0
	global_load_dword v0, v[0:1], off offset:28 sc1
	v_mov_b32_e32 v1, 0x358637bd
	s_mov_b32 s3, 0x800000
	s_waitcnt vmcnt(7)
	v_add_f32_e32 v3, 0, v3
	s_waitcnt vmcnt(6)
	v_add_f32_e32 v3, v3, v4
	s_waitcnt vmcnt(5)
	v_add_f32_e32 v3, v3, v5
	s_waitcnt vmcnt(4)
	v_add_f32_e32 v3, v3, v6
	s_waitcnt vmcnt(3)
	v_add_f32_e32 v3, v3, v7
	s_waitcnt vmcnt(2)
	v_add_f32_e32 v3, v3, v8
	s_waitcnt vmcnt(1)
	v_add_f32_e32 v3, v3, v9
	s_waitcnt vmcnt(0)
	v_add_f32_e32 v0, v3, v0
	v_fmac_f32_e32 v1, 0x3a000000, v0
	v_mul_f32_e32 v0, 0x4b800000, v1
	v_cmp_gt_f32_e32 vcc, s3, v1
	s_nop 1
	v_cndmask_b32_e32 v0, v1, v0, vcc
	v_rsq_f32_e32 v0, v0
	s_nop 0
	v_mul_f32_e32 v1, 0x45800000, v0
	v_cndmask_b32_e32 v0, v0, v1, vcc
	v_lshl_add_u32 v1, v2, 2, 0
	ds_write_b32 v1, v0 offset:4096
